# SwiGLU epilogue fast path (P1,P8): one uniform panel check per unit instead of per row group, rstd table reads hoisted, single 64-bit mad address per row group; original epilogue kept as the slow path
# speedup vs baseline: 1.0069x; 1.0069x over previous
; __device__ __forceinline__ unsigned cvt_pk_bf16(float lo, float hi) { unsigned r; asm volatile("v_cvt_pk_bf16_f32 %0, %1, %2" : "=v"(r) : "v"(lo), "v"(hi)); return r; }
; __device__ __forceinline__ float silu_f(float g) { return g * __builtin_amdgcn_rcpf(1.0f + __expf(-g)); }
; __device__ __forceinline__ f32x2 swiglu_pk(f32x2 g, f32x2 u, float c, float r2) {
;     const f32x2 t = g * c;
;     f32x2 e; e.x = __builtin_amdgcn_exp2f(t.x); e.y = __builtin_amdgcn_exp2f(t.y);
;     const f32x2 d = e + 1.0f;
;     f32x2 s; s.x = __builtin_amdgcn_rcpf(d.x); s.y = __builtin_amdgcn_rcpf(d.y);
;     return (g * u) * (s * r2);
; }
;     __device__ __forceinline__ void operator()(const f32x4 (&acc)[2][2][4][2], const Unit& u, int wr, int wc, int fr, int fq) const {
;         const int row0 = u.pm * BM + wr * 64 + fr, col0 = u.pn * HALF + wc * 32 + 8 * fq; const bool tab = (u.pm == rt_pm);
; #pragma unroll
;         for (int ai = 0; ai < 2; ++ai)
; #pragma unroll
;             for (int m = 0; m < 4; ++m) {
;                 const int row = row0 + ai * HALF + m * 16; const float r = tab ? rtab[row - u.pm * BM] : row_rstd(ss, row);
;                 const float c = r * -1.4426950408889634f, r2 = r * r;
;                 const f32x4 G0 = acc[ai][0][m][0], G1 = acc[ai][0][m][1], U0 = acc[ai][1][m][0], U1 = acc[ai][1][m][1];
;                 const f32x2 h0 = swiglu_pk((f32x2){G0[0], G0[1]}, (f32x2){U0[0], U0[1]}, c, r2), h1 = swiglu_pk((f32x2){G0[2], G0[3]}, (f32x2){U0[2], U0[3]}, c, r2);
;                 const f32x2 h2 = swiglu_pk((f32x2){G1[0], G1[1]}, (f32x2){U1[0], U1[1]}, c, r2), h3 = swiglu_pk((f32x2){G1[2], G1[3]}, (f32x2){U1[2], U1[3]}, c, r2);
;                 u32x4 w;
;                 w.x = cvt_pk_bf16(h0.x, h0.y); w.y = cvt_pk_bf16(h1.x, h1.y); w.z = cvt_pk_bf16(h2.x, h2.y); w.w = cvt_pk_bf16(h3.x, h3.y);
;                 *(u32x4*)(H + (size_t)row * ldh + col0) = w;
.LBB0_137:
	s_cmp_lg_u32 s0, s2
	s_cbranch_scc1 .Lslow_p1
	s_lshl_b32 s15, s0, 8
	v_add_u32_e32 v138, s15, v147
	ds_read_b32 v202, v149
	ds_read_b32 v203, v149 offset:64
	ds_read_b32 v204, v149 offset:128
	ds_read_b32 v205, v149 offset:192
	ds_read_b32 v206, v149 offset:512
	ds_read_b32 v207, v149 offset:576
	ds_read_b32 v208, v149 offset:640
	ds_read_b32 v209, v149 offset:704
	v_lshl_or_b32 v200, s6, 7, v150
	v_mov_b32_e32 v201, 0
	v_lshl_add_u64 v[200:201], v[200:201], 1, s[78:79]
	s_waitcnt lgkmcnt(0)
	v_mov_b32_e32 v168, v202
	v_mul_f32_e32 v170, 0xbfb8aa3b, v168
	v_pk_mul_f32 v[136:137], v[124:125], v[170:171] op_sel_hi:[1,0]
	v_pk_mul_f32 v[178:179], v[126:127], v[170:171] op_sel_hi:[1,0]
	v_exp_f32_e32 v176, v136
	v_exp_f32_e32 v177, v137
	v_exp_f32_e32 v178, v178
	v_exp_f32_e32 v179, v179
	v_pk_mul_f32 v[122:123], v[126:127], v[122:123]
	v_pk_add_f32 v[176:177], v[176:177], 1.0 op_sel_hi:[1,0]
	v_mul_f32_e32 v168, v168, v168
	v_rcp_f32_e32 v176, v176
	v_rcp_f32_e32 v177, v177
	v_pk_add_f32 v[126:127], v[178:179], 1.0 op_sel_hi:[1,0]
	v_pk_mul_f32 v[120:121], v[124:125], v[120:121]
	v_rcp_f32_e32 v126, v126
	v_rcp_f32_e32 v127, v127
	v_pk_mul_f32 v[124:125], v[168:169], v[176:177] op_sel_hi:[0,1]
	v_pk_mul_f32 v[176:177], v[116:117], v[170:171] op_sel_hi:[1,0]
	v_pk_mul_f32 v[120:121], v[120:121], v[124:125]
	v_exp_f32_e32 v176, v176
	v_exp_f32_e32 v177, v177
	v_pk_mul_f32 v[124:125], v[168:169], v[126:127] op_sel_hi:[0,1]
	v_pk_mul_f32 v[126:127], v[118:119], v[170:171] op_sel_hi:[1,0]
	v_pk_mul_f32 v[122:123], v[122:123], v[124:125]
	v_exp_f32_e32 v126, v126
	v_exp_f32_e32 v127, v127
	v_pk_add_f32 v[124:125], v[176:177], 1.0 op_sel_hi:[1,0]
	v_pk_mul_f32 v[114:115], v[118:119], v[114:115]
	v_rcp_f32_e32 v124, v124
	v_rcp_f32_e32 v125, v125
	v_pk_add_f32 v[118:119], v[126:127], 1.0 op_sel_hi:[1,0]
	v_pk_mul_f32 v[112:113], v[116:117], v[112:113]
	v_rcp_f32_e32 v118, v118
	v_rcp_f32_e32 v119, v119
	v_pk_mul_f32 v[116:117], v[168:169], v[124:125] op_sel_hi:[0,1]
	v_pk_mul_f32 v[116:117], v[112:113], v[116:117]
	v_pk_mul_f32 v[112:113], v[168:169], v[118:119] op_sel_hi:[0,1]
	v_pk_mul_f32 v[118:119], v[114:115], v[112:113]
	v_cvt_pk_bf16_f32 v112, v120, v121
	v_cvt_pk_bf16_f32 v113, v122, v123
	v_cvt_pk_bf16_f32 v114, v116, v117
	v_mad_u64_u32 v[116:117], s[0:1], v138, s85, v[200:201]
	v_cvt_pk_bf16_f32 v115, v118, v119
	global_store_dwordx4 v[116:117], v[112:115], off
	s_nop 1
	v_or_b32_e32 v112, 16, v138
	v_mov_b32_e32 v114, v203
	v_mul_f32_e32 v116, 0xbfb8aa3b, v114
	v_pk_mul_f32 v[118:119], v[108:109], v[116:117] op_sel_hi:[1,0]
	v_pk_mul_f32 v[120:121], v[110:111], v[116:117] op_sel_hi:[1,0]
	v_exp_f32_e32 v118, v118
	v_exp_f32_e32 v119, v119
	v_exp_f32_e32 v120, v120
	v_exp_f32_e32 v121, v121
	v_pk_mul_f32 v[106:107], v[110:111], v[106:107]
	v_pk_add_f32 v[118:119], v[118:119], 1.0 op_sel_hi:[1,0]
	v_mul_f32_e32 v114, v114, v114
	v_rcp_f32_e32 v118, v118
	v_rcp_f32_e32 v119, v119
	v_pk_add_f32 v[110:111], v[120:121], 1.0 op_sel_hi:[1,0]
	v_pk_mul_f32 v[104:105], v[108:109], v[104:105]
	v_rcp_f32_e32 v110, v110
	v_rcp_f32_e32 v111, v111
	v_pk_mul_f32 v[108:109], v[114:115], v[118:119] op_sel_hi:[0,1]
	v_pk_mul_f32 v[118:119], v[100:101], v[116:117] op_sel_hi:[1,0]
	v_pk_mul_f32 v[104:105], v[104:105], v[108:109]
	v_exp_f32_e32 v118, v118
	v_exp_f32_e32 v119, v119
	v_pk_mul_f32 v[108:109], v[114:115], v[110:111] op_sel_hi:[0,1]
	v_pk_mul_f32 v[110:111], v[102:103], v[116:117] op_sel_hi:[1,0]
	v_pk_mul_f32 v[106:107], v[106:107], v[108:109]
	v_exp_f32_e32 v110, v110
	v_exp_f32_e32 v111, v111
	v_pk_add_f32 v[108:109], v[118:119], 1.0 op_sel_hi:[1,0]
	v_pk_mul_f32 v[98:99], v[102:103], v[98:99]
	v_rcp_f32_e32 v108, v108
	v_rcp_f32_e32 v109, v109
	v_pk_add_f32 v[102:103], v[110:111], 1.0 op_sel_hi:[1,0]
	v_pk_mul_f32 v[96:97], v[100:101], v[96:97]
	v_rcp_f32_e32 v102, v102
	v_rcp_f32_e32 v103, v103
	v_pk_mul_f32 v[100:101], v[114:115], v[108:109] op_sel_hi:[0,1]
	v_pk_mul_f32 v[100:101], v[96:97], v[100:101]
	v_pk_mul_f32 v[96:97], v[114:115], v[102:103] op_sel_hi:[0,1]
	v_pk_mul_f32 v[102:103], v[98:99], v[96:97]
	v_cvt_pk_bf16_f32 v96, v104, v105
	v_cvt_pk_bf16_f32 v97, v106, v107
	v_cvt_pk_bf16_f32 v98, v100, v101
	v_mad_u64_u32 v[100:101], s[6:7], v112, s85, v[200:201]
	v_cvt_pk_bf16_f32 v99, v102, v103
	global_store_dwordx4 v[100:101], v[96:99], off
	s_nop 1
	s_nop 0
	v_or_b32_e32 v96, 32, v138
	v_mov_b32_e32 v98, v204
	v_mul_f32_e32 v100, 0xbfb8aa3b, v98
	v_pk_mul_f32 v[102:103], v[92:93], v[100:101] op_sel_hi:[1,0]
	v_pk_mul_f32 v[104:105], v[94:95], v[100:101] op_sel_hi:[1,0]
	v_exp_f32_e32 v102, v102
	v_exp_f32_e32 v103, v103
	v_exp_f32_e32 v104, v104
	v_exp_f32_e32 v105, v105
	v_pk_mul_f32 v[90:91], v[94:95], v[90:91]
	v_pk_add_f32 v[102:103], v[102:103], 1.0 op_sel_hi:[1,0]
	v_mul_f32_e32 v98, v98, v98
	v_rcp_f32_e32 v102, v102
	v_rcp_f32_e32 v103, v103
	v_pk_add_f32 v[94:95], v[104:105], 1.0 op_sel_hi:[1,0]
	v_pk_mul_f32 v[88:89], v[92:93], v[88:89]
	v_rcp_f32_e32 v94, v94
	v_rcp_f32_e32 v95, v95
	v_pk_mul_f32 v[92:93], v[98:99], v[102:103] op_sel_hi:[0,1]
	v_pk_mul_f32 v[102:103], v[84:85], v[100:101] op_sel_hi:[1,0]
	v_pk_mul_f32 v[88:89], v[88:89], v[92:93]
	v_exp_f32_e32 v102, v102
	v_exp_f32_e32 v103, v103
	v_pk_mul_f32 v[92:93], v[98:99], v[94:95] op_sel_hi:[0,1]
	v_pk_mul_f32 v[94:95], v[86:87], v[100:101] op_sel_hi:[1,0]
	v_pk_mul_f32 v[90:91], v[90:91], v[92:93]
	v_exp_f32_e32 v94, v94
	v_exp_f32_e32 v95, v95
	v_pk_add_f32 v[92:93], v[102:103], 1.0 op_sel_hi:[1,0]
	v_pk_mul_f32 v[82:83], v[86:87], v[82:83]
	v_rcp_f32_e32 v92, v92
	v_rcp_f32_e32 v93, v93
	v_pk_add_f32 v[86:87], v[94:95], 1.0 op_sel_hi:[1,0]
; __device__ __forceinline__ unsigned cvt_pk_bf16(float lo, float hi) { unsigned r; asm volatile("v_cvt_pk_bf16_f32 %0, %1, %2" : "=v"(r) : "v"(lo), "v"(hi)); return r; }
; __device__ __forceinline__ f32x2 swiglu_pk(f32x2 g, f32x2 u, float c, float r2) {
;     const f32x2 t = g * c;
;     f32x2 e; e.x = __builtin_amdgcn_exp2f(t.x); e.y = __builtin_amdgcn_exp2f(t.y);
;     const f32x2 d = e + 1.0f;
;     f32x2 s; s.x = __builtin_amdgcn_rcpf(d.x); s.y = __builtin_amdgcn_rcpf(d.y);
;     return (g * u) * (s * r2);
; }
;     __device__ __forceinline__ void operator()(const f32x4 (&acc)[2][2][4][2], const Unit& u, int wr, int wc, int fr, int fq) const {
;     ...
;                 const int row = row0 + ai * HALF + m * 16; const float r = tab ? rtab[row - u.pm * BM] : row_rstd(ss, row);
;                 const float c = r * -1.4426950408889634f, r2 = r * r;
;                 const f32x4 G0 = acc[ai][0][m][0], G1 = acc[ai][0][m][1], U0 = acc[ai][1][m][0], U1 = acc[ai][1][m][1];
;                 const f32x2 h0 = swiglu_pk((f32x2){G0[0], G0[1]}, (f32x2){U0[0], U0[1]}, c, r2), h1 = swiglu_pk((f32x2){G0[2], G0[3]}, (f32x2){U0[2], U0[3]}, c, r2);
;                 const f32x2 h2 = swiglu_pk((f32x2){G1[0], G1[1]}, (f32x2){U1[0], U1[1]}, c, r2), h3 = swiglu_pk((f32x2){G1[2], G1[3]}, (f32x2){U1[2], U1[3]}, c, r2);
;                 u32x4 w;
;                 w.x = cvt_pk_bf16(h0.x, h0.y); w.y = cvt_pk_bf16(h1.x, h1.y); w.z = cvt_pk_bf16(h2.x, h2.y); w.w = cvt_pk_bf16(h3.x, h3.y);
;                 *(u32x4*)(H + (size_t)row * ldh + col0) = w;
	v_pk_mul_f32 v[80:81], v[84:85], v[80:81]
	v_rcp_f32_e32 v86, v86
	v_rcp_f32_e32 v87, v87
	v_pk_mul_f32 v[84:85], v[98:99], v[92:93] op_sel_hi:[0,1]
	v_pk_mul_f32 v[84:85], v[80:81], v[84:85]
	v_pk_mul_f32 v[80:81], v[98:99], v[86:87] op_sel_hi:[0,1]
	v_pk_mul_f32 v[86:87], v[82:83], v[80:81]
	v_cvt_pk_bf16_f32 v80, v88, v89
	v_cvt_pk_bf16_f32 v81, v90, v91
	v_cvt_pk_bf16_f32 v82, v84, v85
	v_mad_u64_u32 v[84:85], s[6:7], v96, s85, v[200:201]
	v_cvt_pk_bf16_f32 v83, v86, v87
	global_store_dwordx4 v[84:85], v[80:83], off
	s_nop 1
	s_nop 0
	v_or_b32_e32 v80, 48, v138
	v_mov_b32_e32 v82, v205
	v_mul_f32_e32 v84, 0xbfb8aa3b, v82
	v_pk_mul_f32 v[86:87], v[76:77], v[84:85] op_sel_hi:[1,0]
	v_pk_mul_f32 v[88:89], v[78:79], v[84:85] op_sel_hi:[1,0]
	v_exp_f32_e32 v86, v86
	v_exp_f32_e32 v87, v87
	v_exp_f32_e32 v88, v88
	v_exp_f32_e32 v89, v89
	v_pk_mul_f32 v[74:75], v[78:79], v[74:75]
	v_pk_add_f32 v[86:87], v[86:87], 1.0 op_sel_hi:[1,0]
	v_mul_f32_e32 v82, v82, v82
	v_rcp_f32_e32 v86, v86
	v_rcp_f32_e32 v87, v87
	v_pk_add_f32 v[78:79], v[88:89], 1.0 op_sel_hi:[1,0]
	v_pk_mul_f32 v[72:73], v[76:77], v[72:73]
	v_rcp_f32_e32 v78, v78
	v_rcp_f32_e32 v79, v79
	v_pk_mul_f32 v[76:77], v[82:83], v[86:87] op_sel_hi:[0,1]
	v_pk_mul_f32 v[86:87], v[68:69], v[84:85] op_sel_hi:[1,0]
	v_pk_mul_f32 v[72:73], v[72:73], v[76:77]
	v_exp_f32_e32 v86, v86
	v_exp_f32_e32 v87, v87
	v_pk_mul_f32 v[76:77], v[82:83], v[78:79] op_sel_hi:[0,1]
	v_pk_mul_f32 v[78:79], v[70:71], v[84:85] op_sel_hi:[1,0]
	v_pk_mul_f32 v[74:75], v[74:75], v[76:77]
	v_exp_f32_e32 v78, v78
	v_exp_f32_e32 v79, v79
	v_pk_add_f32 v[76:77], v[86:87], 1.0 op_sel_hi:[1,0]
	v_pk_mul_f32 v[66:67], v[70:71], v[66:67]
	v_rcp_f32_e32 v76, v76
	v_rcp_f32_e32 v77, v77
	v_pk_add_f32 v[70:71], v[78:79], 1.0 op_sel_hi:[1,0]
	v_pk_mul_f32 v[64:65], v[68:69], v[64:65]
	v_rcp_f32_e32 v70, v70
	v_rcp_f32_e32 v71, v71
	v_pk_mul_f32 v[68:69], v[82:83], v[76:77] op_sel_hi:[0,1]
	v_pk_mul_f32 v[68:69], v[64:65], v[68:69]
	v_pk_mul_f32 v[64:65], v[82:83], v[70:71] op_sel_hi:[0,1]
	v_pk_mul_f32 v[70:71], v[66:67], v[64:65]
	v_cvt_pk_bf16_f32 v64, v72, v73
	v_cvt_pk_bf16_f32 v65, v74, v75
	v_cvt_pk_bf16_f32 v66, v68, v69
	v_mad_u64_u32 v[68:69], s[6:7], v80, s85, v[200:201]
	v_cvt_pk_bf16_f32 v67, v70, v71
	global_store_dwordx4 v[68:69], v[64:67], off
	s_nop 1
	s_nop 0
	v_add_u32_e32 v64, 0x80, v138
	v_mov_b32_e32 v66, v206
	v_mul_f32_e32 v68, 0xbfb8aa3b, v66
	v_pk_mul_f32 v[70:71], v[60:61], v[68:69] op_sel_hi:[1,0]
	v_pk_mul_f32 v[72:73], v[62:63], v[68:69] op_sel_hi:[1,0]
	v_exp_f32_e32 v70, v70
	v_exp_f32_e32 v71, v71
	v_exp_f32_e32 v72, v72
	v_exp_f32_e32 v73, v73
	v_pk_mul_f32 v[58:59], v[62:63], v[58:59]
	v_pk_add_f32 v[70:71], v[70:71], 1.0 op_sel_hi:[1,0]
	v_mul_f32_e32 v66, v66, v66
	v_rcp_f32_e32 v70, v70
	v_rcp_f32_e32 v71, v71
	v_pk_add_f32 v[62:63], v[72:73], 1.0 op_sel_hi:[1,0]
	v_pk_mul_f32 v[56:57], v[60:61], v[56:57]
	v_rcp_f32_e32 v62, v62
	v_rcp_f32_e32 v63, v63
	v_pk_mul_f32 v[60:61], v[66:67], v[70:71] op_sel_hi:[0,1]
	v_pk_mul_f32 v[70:71], v[52:53], v[68:69] op_sel_hi:[1,0]
	v_pk_mul_f32 v[56:57], v[56:57], v[60:61]
	v_exp_f32_e32 v70, v70
	v_exp_f32_e32 v71, v71
	v_pk_mul_f32 v[60:61], v[66:67], v[62:63] op_sel_hi:[0,1]
	v_pk_mul_f32 v[62:63], v[54:55], v[68:69] op_sel_hi:[1,0]
	v_pk_mul_f32 v[58:59], v[58:59], v[60:61]
	v_exp_f32_e32 v62, v62
	v_exp_f32_e32 v63, v63
	v_pk_add_f32 v[60:61], v[70:71], 1.0 op_sel_hi:[1,0]
	v_pk_mul_f32 v[50:51], v[54:55], v[50:51]
	v_rcp_f32_e32 v60, v60
	v_rcp_f32_e32 v61, v61
	v_pk_add_f32 v[54:55], v[62:63], 1.0 op_sel_hi:[1,0]
	v_pk_mul_f32 v[48:49], v[52:53], v[48:49]
	v_rcp_f32_e32 v54, v54
	v_rcp_f32_e32 v55, v55
	v_pk_mul_f32 v[52:53], v[66:67], v[60:61] op_sel_hi:[0,1]
	v_pk_mul_f32 v[52:53], v[48:49], v[52:53]
	v_pk_mul_f32 v[48:49], v[66:67], v[54:55] op_sel_hi:[0,1]
	v_pk_mul_f32 v[54:55], v[50:51], v[48:49]
	v_cvt_pk_bf16_f32 v48, v56, v57
	v_cvt_pk_bf16_f32 v49, v58, v59
	v_cvt_pk_bf16_f32 v50, v52, v53
	v_mad_u64_u32 v[52:53], s[6:7], v64, s85, v[200:201]
	v_cvt_pk_bf16_f32 v51, v54, v55
	global_store_dwordx4 v[52:53], v[48:51], off
	s_nop 1
	s_nop 0
	v_add_u32_e32 v48, 0x90, v138
	v_mov_b32_e32 v50, v207
	v_mul_f32_e32 v52, 0xbfb8aa3b, v50
	v_pk_mul_f32 v[54:55], v[44:45], v[52:53] op_sel_hi:[1,0]
	v_pk_mul_f32 v[56:57], v[46:47], v[52:53] op_sel_hi:[1,0]
	v_exp_f32_e32 v54, v54
	v_exp_f32_e32 v55, v55
	v_exp_f32_e32 v56, v56
	v_exp_f32_e32 v57, v57
	v_pk_mul_f32 v[42:43], v[46:47], v[42:43]
	v_pk_add_f32 v[54:55], v[54:55], 1.0 op_sel_hi:[1,0]
	v_mul_f32_e32 v50, v50, v50
	v_rcp_f32_e32 v54, v54
	v_rcp_f32_e32 v55, v55
	v_pk_add_f32 v[46:47], v[56:57], 1.0 op_sel_hi:[1,0]
	v_pk_mul_f32 v[40:41], v[44:45], v[40:41]
	v_rcp_f32_e32 v46, v46
	v_rcp_f32_e32 v47, v47
; __device__ __forceinline__ unsigned cvt_pk_bf16(float lo, float hi) { unsigned r; asm volatile("v_cvt_pk_bf16_f32 %0, %1, %2" : "=v"(r) : "v"(lo), "v"(hi)); return r; }
; __device__ __forceinline__ f32x2 swiglu_pk(f32x2 g, f32x2 u, float c, float r2) {
;     const f32x2 t = g * c;
;     f32x2 e; e.x = __builtin_amdgcn_exp2f(t.x); e.y = __builtin_amdgcn_exp2f(t.y);
;     const f32x2 d = e + 1.0f;
;     f32x2 s; s.x = __builtin_amdgcn_rcpf(d.x); s.y = __builtin_amdgcn_rcpf(d.y);
;     return (g * u) * (s * r2);
; }
;     __device__ __forceinline__ void operator()(const f32x4 (&acc)[2][2][4][2], const Unit& u, int wr, int wc, int fr, int fq) const {
;     ...
;                 const int row = row0 + ai * HALF + m * 16; const float r = tab ? rtab[row - u.pm * BM] : row_rstd(ss, row);
;                 const float c = r * -1.4426950408889634f, r2 = r * r;
;                 const f32x4 G0 = acc[ai][0][m][0], G1 = acc[ai][0][m][1], U0 = acc[ai][1][m][0], U1 = acc[ai][1][m][1];
;                 const f32x2 h0 = swiglu_pk((f32x2){G0[0], G0[1]}, (f32x2){U0[0], U0[1]}, c, r2), h1 = swiglu_pk((f32x2){G0[2], G0[3]}, (f32x2){U0[2], U0[3]}, c, r2);
;                 const f32x2 h2 = swiglu_pk((f32x2){G1[0], G1[1]}, (f32x2){U1[0], U1[1]}, c, r2), h3 = swiglu_pk((f32x2){G1[2], G1[3]}, (f32x2){U1[2], U1[3]}, c, r2);
;                 u32x4 w;
;                 w.x = cvt_pk_bf16(h0.x, h0.y); w.y = cvt_pk_bf16(h1.x, h1.y); w.z = cvt_pk_bf16(h2.x, h2.y); w.w = cvt_pk_bf16(h3.x, h3.y);
;                 *(u32x4*)(H + (size_t)row * ldh + col0) = w;
	v_pk_mul_f32 v[44:45], v[50:51], v[54:55] op_sel_hi:[0,1]
	v_pk_mul_f32 v[54:55], v[36:37], v[52:53] op_sel_hi:[1,0]
	v_pk_mul_f32 v[40:41], v[40:41], v[44:45]
	v_exp_f32_e32 v54, v54
	v_exp_f32_e32 v55, v55
	v_pk_mul_f32 v[44:45], v[50:51], v[46:47] op_sel_hi:[0,1]
	v_pk_mul_f32 v[46:47], v[38:39], v[52:53] op_sel_hi:[1,0]
	v_pk_mul_f32 v[42:43], v[42:43], v[44:45]
	v_exp_f32_e32 v46, v46
	v_exp_f32_e32 v47, v47
	v_pk_add_f32 v[44:45], v[54:55], 1.0 op_sel_hi:[1,0]
	v_pk_mul_f32 v[34:35], v[38:39], v[34:35]
	v_rcp_f32_e32 v44, v44
	v_rcp_f32_e32 v45, v45
	v_pk_add_f32 v[38:39], v[46:47], 1.0 op_sel_hi:[1,0]
	v_pk_mul_f32 v[32:33], v[36:37], v[32:33]
	v_rcp_f32_e32 v38, v38
	v_rcp_f32_e32 v39, v39
	v_pk_mul_f32 v[36:37], v[50:51], v[44:45] op_sel_hi:[0,1]
	v_pk_mul_f32 v[36:37], v[32:33], v[36:37]
	v_pk_mul_f32 v[32:33], v[50:51], v[38:39] op_sel_hi:[0,1]
	v_pk_mul_f32 v[38:39], v[34:35], v[32:33]
	v_cvt_pk_bf16_f32 v32, v40, v41
	v_cvt_pk_bf16_f32 v33, v42, v43
	v_cvt_pk_bf16_f32 v34, v36, v37
	v_mad_u64_u32 v[36:37], s[6:7], v48, s85, v[200:201]
	v_cvt_pk_bf16_f32 v35, v38, v39
	global_store_dwordx4 v[36:37], v[32:35], off
	s_nop 1
	s_nop 0
	v_add_u32_e32 v32, 0xa0, v138
	v_mov_b32_e32 v34, v208
	v_mul_f32_e32 v36, 0xbfb8aa3b, v34
	v_pk_mul_f32 v[38:39], v[28:29], v[36:37] op_sel_hi:[1,0]
	v_pk_mul_f32 v[40:41], v[30:31], v[36:37] op_sel_hi:[1,0]
	v_exp_f32_e32 v38, v38
	v_exp_f32_e32 v39, v39
	v_exp_f32_e32 v40, v40
	v_exp_f32_e32 v41, v41
	v_pk_mul_f32 v[26:27], v[30:31], v[26:27]
	v_pk_add_f32 v[38:39], v[38:39], 1.0 op_sel_hi:[1,0]
	v_mul_f32_e32 v34, v34, v34
	v_rcp_f32_e32 v38, v38
	v_rcp_f32_e32 v39, v39
	v_pk_add_f32 v[30:31], v[40:41], 1.0 op_sel_hi:[1,0]
	v_pk_mul_f32 v[24:25], v[28:29], v[24:25]
	v_rcp_f32_e32 v30, v30
	v_rcp_f32_e32 v31, v31
	v_pk_mul_f32 v[28:29], v[34:35], v[38:39] op_sel_hi:[0,1]
	v_pk_mul_f32 v[38:39], v[20:21], v[36:37] op_sel_hi:[1,0]
	v_pk_mul_f32 v[24:25], v[24:25], v[28:29]
	v_exp_f32_e32 v38, v38
	v_exp_f32_e32 v39, v39
	v_pk_mul_f32 v[28:29], v[34:35], v[30:31] op_sel_hi:[0,1]
	v_pk_mul_f32 v[30:31], v[22:23], v[36:37] op_sel_hi:[1,0]
	v_pk_mul_f32 v[26:27], v[26:27], v[28:29]
	v_exp_f32_e32 v30, v30
	v_exp_f32_e32 v31, v31
	v_pk_add_f32 v[28:29], v[38:39], 1.0 op_sel_hi:[1,0]
	v_pk_mul_f32 v[18:19], v[22:23], v[18:19]
	v_rcp_f32_e32 v28, v28
	v_rcp_f32_e32 v29, v29
	v_pk_add_f32 v[22:23], v[30:31], 1.0 op_sel_hi:[1,0]
	v_pk_mul_f32 v[16:17], v[20:21], v[16:17]
	v_rcp_f32_e32 v22, v22
	v_rcp_f32_e32 v23, v23
	v_pk_mul_f32 v[20:21], v[34:35], v[28:29] op_sel_hi:[0,1]
	v_pk_mul_f32 v[20:21], v[16:17], v[20:21]
	v_pk_mul_f32 v[16:17], v[34:35], v[22:23] op_sel_hi:[0,1]
	v_pk_mul_f32 v[22:23], v[18:19], v[16:17]
	v_cvt_pk_bf16_f32 v16, v24, v25
	v_cvt_pk_bf16_f32 v17, v26, v27
	v_cvt_pk_bf16_f32 v18, v20, v21
	v_mad_u64_u32 v[20:21], s[6:7], v32, s85, v[200:201]
	v_cvt_pk_bf16_f32 v19, v22, v23
	global_store_dwordx4 v[20:21], v[16:19], off
	s_nop 1
	s_nop 0
	v_add_u32_e32 v16, 0xb0, v138
	v_mov_b32_e32 v18, v209
	v_mul_f32_e32 v20, 0xbfb8aa3b, v18
	v_pk_mul_f32 v[22:23], v[12:13], v[20:21] op_sel_hi:[1,0]
	v_pk_mul_f32 v[24:25], v[14:15], v[20:21] op_sel_hi:[1,0]
	v_exp_f32_e32 v22, v22
	v_exp_f32_e32 v23, v23
	v_exp_f32_e32 v24, v24
	v_exp_f32_e32 v25, v25
	v_pk_mul_f32 v[10:11], v[14:15], v[10:11]
	v_pk_add_f32 v[22:23], v[22:23], 1.0 op_sel_hi:[1,0]
	v_mul_f32_e32 v18, v18, v18
	v_rcp_f32_e32 v22, v22
	v_rcp_f32_e32 v23, v23
	v_pk_add_f32 v[14:15], v[24:25], 1.0 op_sel_hi:[1,0]
	v_pk_mul_f32 v[8:9], v[12:13], v[8:9]
	v_rcp_f32_e32 v14, v14
	v_rcp_f32_e32 v15, v15
	v_pk_mul_f32 v[12:13], v[18:19], v[22:23] op_sel_hi:[0,1]
	v_pk_mul_f32 v[22:23], v[4:5], v[20:21] op_sel_hi:[1,0]
	v_pk_mul_f32 v[8:9], v[8:9], v[12:13]
	v_exp_f32_e32 v22, v22
	v_exp_f32_e32 v23, v23
	v_pk_mul_f32 v[12:13], v[18:19], v[14:15] op_sel_hi:[0,1]
	v_pk_mul_f32 v[14:15], v[6:7], v[20:21] op_sel_hi:[1,0]
	v_pk_mul_f32 v[10:11], v[10:11], v[12:13]
	v_exp_f32_e32 v14, v14
	v_exp_f32_e32 v15, v15
	v_pk_add_f32 v[12:13], v[22:23], 1.0 op_sel_hi:[1,0]
	v_pk_mul_f32 v[2:3], v[6:7], v[2:3]
	v_rcp_f32_e32 v12, v12
	v_rcp_f32_e32 v13, v13
	v_pk_add_f32 v[6:7], v[14:15], 1.0 op_sel_hi:[1,0]
	v_pk_mul_f32 v[0:1], v[4:5], v[0:1]
	v_rcp_f32_e32 v6, v6
	v_rcp_f32_e32 v7, v7
	v_pk_mul_f32 v[4:5], v[18:19], v[12:13] op_sel_hi:[0,1]
	v_pk_mul_f32 v[4:5], v[0:1], v[4:5]
	s_andn2_b64 vcc, exec, s[4:5]
	v_pk_mul_f32 v[0:1], v[18:19], v[6:7] op_sel_hi:[0,1]
	v_pk_mul_f32 v[6:7], v[2:3], v[0:1]
	v_cvt_pk_bf16_f32 v0, v8, v9
	v_cvt_pk_bf16_f32 v1, v10, v11
	v_cvt_pk_bf16_f32 v2, v4, v5
	v_mad_u64_u32 v[4:5], s[0:1], v16, s85, v[200:201]
	v_cvt_pk_bf16_f32 v3, v6, v7
	s_mov_b64 s[0:1], -1
	global_store_dwordx4 v[4:5], v[0:3], off
	s_nop 1
	s_branch .Ljoin_p1

; #define PG8_BAR __builtin_amdgcn_s_barrier()
; template <class Epi, class Sched, bool ALIGN_EPI = false, bool SP2 = false>
; __device__ __forceinline__ void gemm_phase(PG8_LAS unsigned char* lds, const Gemm g, const Sched& S, const Epi& E) {
;     ...
;         if (!has_next) break;
; #pragma unroll
;         for (int a = 0; a < 2; ++a)
; #pragma unroll
;             for (int b = 0; b < 2; ++b)
; #pragma unroll
;                 for (int m = 0; m < 4; ++m)
; #pragma unroll
;                     for (int n = 0; n < 2; ++n) acc[a][b][m][n] = (f32x4){0.f, 0.f, 0.f, 0.f};
;         cur = nxt; cA = nA; cB = nB; ++ui;
;         if constexpr (ALIGN_EPI) { if (wr == 1) PG8_BAR; }
.Ljoin_p1:
	s_cbranch_vccnz .LBB0_130
	s_andn2_b64 vcc, exec, s[8:9]
	s_cbranch_vccnz .LBB0_129
	s_barrier
	s_branch .LBB0_129

; __device__ __forceinline__ unsigned cvt_pk_bf16(float lo, float hi) { unsigned r; asm volatile("v_cvt_pk_bf16_f32 %0, %1, %2" : "=v"(r) : "v"(lo), "v"(hi)); return r; }
; __device__ __forceinline__ f32x2 swiglu_pk(f32x2 g, f32x2 u, float c, float r2) {
;     const f32x2 t = g * c;
;     f32x2 e; e.x = __builtin_amdgcn_exp2f(t.x); e.y = __builtin_amdgcn_exp2f(t.y);
;     const f32x2 d = e + 1.0f;
;     f32x2 s; s.x = __builtin_amdgcn_rcpf(d.x); s.y = __builtin_amdgcn_rcpf(d.y);
;     return (g * u) * (s * r2);
; }
;     __device__ __forceinline__ void operator()(const f32x4 (&acc)[2][2][4][2], const Unit& u, int wr, int wc, int fr, int fq) const {
;         const int row0 = u.pm * BM + wr * 64 + fr, col0 = u.pn * HALF + wc * 32 + 8 * fq; const bool tab = (u.pm == rt_pm);
; #pragma unroll
;         for (int ai = 0; ai < 2; ++ai)
; #pragma unroll
;             for (int m = 0; m < 4; ++m) {
;                 const int row = row0 + ai * HALF + m * 16; const float r = tab ? rtab[row - u.pm * BM] : row_rstd(ss, row);
;                 const float c = r * -1.4426950408889634f, r2 = r * r;
;                 const f32x4 G0 = acc[ai][0][m][0], G1 = acc[ai][0][m][1], U0 = acc[ai][1][m][0], U1 = acc[ai][1][m][1];
;                 const f32x2 h0 = swiglu_pk((f32x2){G0[0], G0[1]}, (f32x2){U0[0], U0[1]}, c, r2), h1 = swiglu_pk((f32x2){G0[2], G0[3]}, (f32x2){U0[2], U0[3]}, c, r2);
;                 const f32x2 h2 = swiglu_pk((f32x2){G1[0], G1[1]}, (f32x2){U1[0], U1[1]}, c, r2), h3 = swiglu_pk((f32x2){G1[2], G1[3]}, (f32x2){U1[2], U1[3]}, c, r2);
;                 u32x4 w;
;                 w.x = cvt_pk_bf16(h0.x, h0.y); w.y = cvt_pk_bf16(h1.x, h1.y); w.z = cvt_pk_bf16(h2.x, h2.y); w.w = cvt_pk_bf16(h3.x, h3.y);
;                 *(u32x4*)(H + (size_t)row * ldh + col0) = w;
.LBB0_1325:
	s_cmp_lg_u32 s0, s2
	s_cbranch_scc1 .Lslow_p8
	s_lshl_b32 s17, s0, 8
	v_add_u32_e32 v138, s17, v140
	ds_read_b32 v202, v142
	ds_read_b32 v203, v142 offset:64
	ds_read_b32 v204, v142 offset:128
	ds_read_b32 v205, v142 offset:192
	ds_read_b32 v206, v142 offset:512
	ds_read_b32 v207, v142 offset:576
	ds_read_b32 v208, v142 offset:640
	ds_read_b32 v209, v142 offset:704
	v_lshl_or_b32 v200, s10, 7, v143
	v_mov_b32_e32 v201, 0
	v_lshl_add_u64 v[200:201], v[200:201], 1, s[78:79]
	s_waitcnt lgkmcnt(0)
	v_mov_b32_e32 v149, v202
	v_mul_f32_e32 v150, 0xbfb8aa3b, v149
	v_pk_mul_f32 v[136:137], v[124:125], v[150:151] op_sel_hi:[1,0]
	v_pk_mul_f32 v[178:179], v[126:127], v[150:151] op_sel_hi:[1,0]
	v_exp_f32_e32 v174, v136
	v_exp_f32_e32 v175, v137
	v_exp_f32_e32 v178, v178
	v_exp_f32_e32 v179, v179
	v_pk_mul_f32 v[122:123], v[126:127], v[122:123]
	v_pk_add_f32 v[174:175], v[174:175], 1.0 op_sel_hi:[1,0]
	v_mul_f32_e32 v176, v149, v149
	v_rcp_f32_e32 v174, v174
	v_rcp_f32_e32 v175, v175
	v_pk_add_f32 v[126:127], v[178:179], 1.0 op_sel_hi:[1,0]
	v_pk_mul_f32 v[120:121], v[124:125], v[120:121]
	v_rcp_f32_e32 v126, v126
	v_rcp_f32_e32 v127, v127
	v_pk_mul_f32 v[124:125], v[176:177], v[174:175] op_sel_hi:[0,1]
	v_pk_mul_f32 v[174:175], v[116:117], v[150:151] op_sel_hi:[1,0]
	v_pk_mul_f32 v[120:121], v[120:121], v[124:125]
	v_exp_f32_e32 v174, v174
	v_exp_f32_e32 v175, v175
	v_pk_mul_f32 v[124:125], v[176:177], v[126:127] op_sel_hi:[0,1]
	v_pk_mul_f32 v[126:127], v[118:119], v[150:151] op_sel_hi:[1,0]
	v_pk_mul_f32 v[122:123], v[122:123], v[124:125]
	v_exp_f32_e32 v126, v126
	v_exp_f32_e32 v127, v127
	v_pk_add_f32 v[124:125], v[174:175], 1.0 op_sel_hi:[1,0]
	v_pk_mul_f32 v[114:115], v[118:119], v[114:115]
	v_rcp_f32_e32 v124, v124
	v_rcp_f32_e32 v125, v125
	v_pk_add_f32 v[118:119], v[126:127], 1.0 op_sel_hi:[1,0]
	v_pk_mul_f32 v[112:113], v[116:117], v[112:113]
	v_rcp_f32_e32 v118, v118
	v_rcp_f32_e32 v119, v119
	v_pk_mul_f32 v[116:117], v[176:177], v[124:125] op_sel_hi:[0,1]
	v_pk_mul_f32 v[116:117], v[112:113], v[116:117]
	v_pk_mul_f32 v[112:113], v[176:177], v[118:119] op_sel_hi:[0,1]
	v_pk_mul_f32 v[118:119], v[114:115], v[112:113]
	v_cvt_pk_bf16_f32 v112, v120, v121
	v_cvt_pk_bf16_f32 v113, v122, v123
	v_cvt_pk_bf16_f32 v114, v116, v117
	v_mad_u64_u32 v[116:117], s[0:1], v138, s47, v[200:201]
	v_cvt_pk_bf16_f32 v115, v118, v119
	global_store_dwordx4 v[116:117], v[112:115], off
	s_nop 1
	v_or_b32_e32 v112, 16, v138
	v_mov_b32_e32 v114, v203
	v_mul_f32_e32 v116, 0xbfb8aa3b, v114
	v_pk_mul_f32 v[118:119], v[108:109], v[116:117] op_sel_hi:[1,0]
	v_pk_mul_f32 v[120:121], v[110:111], v[116:117] op_sel_hi:[1,0]
	v_exp_f32_e32 v118, v118
	v_exp_f32_e32 v119, v119
	v_exp_f32_e32 v120, v120
	v_exp_f32_e32 v121, v121
	v_pk_mul_f32 v[106:107], v[110:111], v[106:107]
	v_pk_add_f32 v[118:119], v[118:119], 1.0 op_sel_hi:[1,0]
	v_mul_f32_e32 v114, v114, v114
	v_rcp_f32_e32 v118, v118
	v_rcp_f32_e32 v119, v119
	v_pk_add_f32 v[110:111], v[120:121], 1.0 op_sel_hi:[1,0]
	v_pk_mul_f32 v[104:105], v[108:109], v[104:105]
	v_rcp_f32_e32 v110, v110
	v_rcp_f32_e32 v111, v111
	v_pk_mul_f32 v[108:109], v[114:115], v[118:119] op_sel_hi:[0,1]
	v_pk_mul_f32 v[118:119], v[100:101], v[116:117] op_sel_hi:[1,0]
	v_pk_mul_f32 v[104:105], v[104:105], v[108:109]
	v_exp_f32_e32 v118, v118
	v_exp_f32_e32 v119, v119
	v_pk_mul_f32 v[108:109], v[114:115], v[110:111] op_sel_hi:[0,1]
	v_pk_mul_f32 v[110:111], v[102:103], v[116:117] op_sel_hi:[1,0]
	v_pk_mul_f32 v[106:107], v[106:107], v[108:109]
	v_exp_f32_e32 v110, v110
	v_exp_f32_e32 v111, v111
	v_pk_add_f32 v[108:109], v[118:119], 1.0 op_sel_hi:[1,0]
	v_pk_mul_f32 v[98:99], v[102:103], v[98:99]
	v_rcp_f32_e32 v108, v108
	v_rcp_f32_e32 v109, v109
	v_pk_add_f32 v[102:103], v[110:111], 1.0 op_sel_hi:[1,0]
	v_pk_mul_f32 v[96:97], v[100:101], v[96:97]
	v_rcp_f32_e32 v102, v102
	v_rcp_f32_e32 v103, v103
	v_pk_mul_f32 v[100:101], v[114:115], v[108:109] op_sel_hi:[0,1]
	v_pk_mul_f32 v[100:101], v[96:97], v[100:101]
	v_pk_mul_f32 v[96:97], v[114:115], v[102:103] op_sel_hi:[0,1]
	v_pk_mul_f32 v[102:103], v[98:99], v[96:97]
	v_cvt_pk_bf16_f32 v96, v104, v105
	v_cvt_pk_bf16_f32 v97, v106, v107
	v_cvt_pk_bf16_f32 v98, v100, v101
	v_mad_u64_u32 v[100:101], s[10:11], v112, s47, v[200:201]
	v_cvt_pk_bf16_f32 v99, v102, v103
	global_store_dwordx4 v[100:101], v[96:99], off
	s_nop 1
	s_nop 0
	v_or_b32_e32 v96, 32, v138
	v_mov_b32_e32 v98, v204
	v_mul_f32_e32 v100, 0xbfb8aa3b, v98
	v_pk_mul_f32 v[102:103], v[92:93], v[100:101] op_sel_hi:[1,0]
	v_pk_mul_f32 v[104:105], v[94:95], v[100:101] op_sel_hi:[1,0]
	v_exp_f32_e32 v102, v102
	v_exp_f32_e32 v103, v103
	v_exp_f32_e32 v104, v104
	v_exp_f32_e32 v105, v105
	v_pk_mul_f32 v[90:91], v[94:95], v[90:91]
	v_pk_add_f32 v[102:103], v[102:103], 1.0 op_sel_hi:[1,0]
	v_mul_f32_e32 v98, v98, v98
	v_rcp_f32_e32 v102, v102
	v_rcp_f32_e32 v103, v103
	v_pk_add_f32 v[94:95], v[104:105], 1.0 op_sel_hi:[1,0]
	v_pk_mul_f32 v[88:89], v[92:93], v[88:89]
	v_rcp_f32_e32 v94, v94
	v_rcp_f32_e32 v95, v95
	v_pk_mul_f32 v[92:93], v[98:99], v[102:103] op_sel_hi:[0,1]
	v_pk_mul_f32 v[102:103], v[84:85], v[100:101] op_sel_hi:[1,0]
	v_pk_mul_f32 v[88:89], v[88:89], v[92:93]
	v_exp_f32_e32 v102, v102
	v_exp_f32_e32 v103, v103
	v_pk_mul_f32 v[92:93], v[98:99], v[94:95] op_sel_hi:[0,1]
	v_pk_mul_f32 v[94:95], v[86:87], v[100:101] op_sel_hi:[1,0]
	v_pk_mul_f32 v[90:91], v[90:91], v[92:93]
	v_exp_f32_e32 v94, v94
	v_exp_f32_e32 v95, v95
	v_pk_add_f32 v[92:93], v[102:103], 1.0 op_sel_hi:[1,0]
	v_pk_mul_f32 v[82:83], v[86:87], v[82:83]
	v_rcp_f32_e32 v92, v92
	v_rcp_f32_e32 v93, v93
	v_pk_add_f32 v[86:87], v[94:95], 1.0 op_sel_hi:[1,0]
; __device__ __forceinline__ unsigned cvt_pk_bf16(float lo, float hi) { unsigned r; asm volatile("v_cvt_pk_bf16_f32 %0, %1, %2" : "=v"(r) : "v"(lo), "v"(hi)); return r; }
; __device__ __forceinline__ f32x2 swiglu_pk(f32x2 g, f32x2 u, float c, float r2) {
;     const f32x2 t = g * c;
;     f32x2 e; e.x = __builtin_amdgcn_exp2f(t.x); e.y = __builtin_amdgcn_exp2f(t.y);
;     const f32x2 d = e + 1.0f;
;     f32x2 s; s.x = __builtin_amdgcn_rcpf(d.x); s.y = __builtin_amdgcn_rcpf(d.y);
;     return (g * u) * (s * r2);
; }
;     __device__ __forceinline__ void operator()(const f32x4 (&acc)[2][2][4][2], const Unit& u, int wr, int wc, int fr, int fq) const {
;     ...
;                 const int row = row0 + ai * HALF + m * 16; const float r = tab ? rtab[row - u.pm * BM] : row_rstd(ss, row);
;                 const float c = r * -1.4426950408889634f, r2 = r * r;
;                 const f32x4 G0 = acc[ai][0][m][0], G1 = acc[ai][0][m][1], U0 = acc[ai][1][m][0], U1 = acc[ai][1][m][1];
;                 const f32x2 h0 = swiglu_pk((f32x2){G0[0], G0[1]}, (f32x2){U0[0], U0[1]}, c, r2), h1 = swiglu_pk((f32x2){G0[2], G0[3]}, (f32x2){U0[2], U0[3]}, c, r2);
;                 const f32x2 h2 = swiglu_pk((f32x2){G1[0], G1[1]}, (f32x2){U1[0], U1[1]}, c, r2), h3 = swiglu_pk((f32x2){G1[2], G1[3]}, (f32x2){U1[2], U1[3]}, c, r2);
;                 u32x4 w;
;                 w.x = cvt_pk_bf16(h0.x, h0.y); w.y = cvt_pk_bf16(h1.x, h1.y); w.z = cvt_pk_bf16(h2.x, h2.y); w.w = cvt_pk_bf16(h3.x, h3.y);
;                 *(u32x4*)(H + (size_t)row * ldh + col0) = w;
	v_pk_mul_f32 v[80:81], v[84:85], v[80:81]
	v_rcp_f32_e32 v86, v86
	v_rcp_f32_e32 v87, v87
	v_pk_mul_f32 v[84:85], v[98:99], v[92:93] op_sel_hi:[0,1]
	v_pk_mul_f32 v[84:85], v[80:81], v[84:85]
	v_pk_mul_f32 v[80:81], v[98:99], v[86:87] op_sel_hi:[0,1]
	v_pk_mul_f32 v[86:87], v[82:83], v[80:81]
	v_cvt_pk_bf16_f32 v80, v88, v89
	v_cvt_pk_bf16_f32 v81, v90, v91
	v_cvt_pk_bf16_f32 v82, v84, v85
	v_mad_u64_u32 v[84:85], s[10:11], v96, s47, v[200:201]
	v_cvt_pk_bf16_f32 v83, v86, v87
	global_store_dwordx4 v[84:85], v[80:83], off
	s_nop 1
	s_nop 0
	v_or_b32_e32 v80, 48, v138
	v_mov_b32_e32 v82, v205
	v_mul_f32_e32 v84, 0xbfb8aa3b, v82
	v_pk_mul_f32 v[86:87], v[76:77], v[84:85] op_sel_hi:[1,0]
	v_pk_mul_f32 v[88:89], v[78:79], v[84:85] op_sel_hi:[1,0]
	v_exp_f32_e32 v86, v86
	v_exp_f32_e32 v87, v87
	v_exp_f32_e32 v88, v88
	v_exp_f32_e32 v89, v89
	v_pk_mul_f32 v[74:75], v[78:79], v[74:75]
	v_pk_add_f32 v[86:87], v[86:87], 1.0 op_sel_hi:[1,0]
	v_mul_f32_e32 v82, v82, v82
	v_rcp_f32_e32 v86, v86
	v_rcp_f32_e32 v87, v87
	v_pk_add_f32 v[78:79], v[88:89], 1.0 op_sel_hi:[1,0]
	v_pk_mul_f32 v[72:73], v[76:77], v[72:73]
	v_rcp_f32_e32 v78, v78
	v_rcp_f32_e32 v79, v79
	v_pk_mul_f32 v[76:77], v[82:83], v[86:87] op_sel_hi:[0,1]
	v_pk_mul_f32 v[86:87], v[68:69], v[84:85] op_sel_hi:[1,0]
	v_pk_mul_f32 v[72:73], v[72:73], v[76:77]
	v_exp_f32_e32 v86, v86
	v_exp_f32_e32 v87, v87
	v_pk_mul_f32 v[76:77], v[82:83], v[78:79] op_sel_hi:[0,1]
	v_pk_mul_f32 v[78:79], v[70:71], v[84:85] op_sel_hi:[1,0]
	v_pk_mul_f32 v[74:75], v[74:75], v[76:77]
	v_exp_f32_e32 v78, v78
	v_exp_f32_e32 v79, v79
	v_pk_add_f32 v[76:77], v[86:87], 1.0 op_sel_hi:[1,0]
	v_pk_mul_f32 v[66:67], v[70:71], v[66:67]
	v_rcp_f32_e32 v76, v76
	v_rcp_f32_e32 v77, v77
	v_pk_add_f32 v[70:71], v[78:79], 1.0 op_sel_hi:[1,0]
	v_pk_mul_f32 v[64:65], v[68:69], v[64:65]
	v_rcp_f32_e32 v70, v70
	v_rcp_f32_e32 v71, v71
	v_pk_mul_f32 v[68:69], v[82:83], v[76:77] op_sel_hi:[0,1]
	v_pk_mul_f32 v[68:69], v[64:65], v[68:69]
	v_pk_mul_f32 v[64:65], v[82:83], v[70:71] op_sel_hi:[0,1]
	v_pk_mul_f32 v[70:71], v[66:67], v[64:65]
	v_cvt_pk_bf16_f32 v64, v72, v73
	v_cvt_pk_bf16_f32 v65, v74, v75
	v_cvt_pk_bf16_f32 v66, v68, v69
	v_mad_u64_u32 v[68:69], s[10:11], v80, s47, v[200:201]
	v_cvt_pk_bf16_f32 v67, v70, v71
	global_store_dwordx4 v[68:69], v[64:67], off
	s_nop 1
	s_nop 0
	v_add_u32_e32 v64, 0x80, v138
	v_mov_b32_e32 v66, v206
	v_mul_f32_e32 v68, 0xbfb8aa3b, v66
	v_pk_mul_f32 v[70:71], v[60:61], v[68:69] op_sel_hi:[1,0]
	v_pk_mul_f32 v[72:73], v[62:63], v[68:69] op_sel_hi:[1,0]
	v_exp_f32_e32 v70, v70
	v_exp_f32_e32 v71, v71
	v_exp_f32_e32 v72, v72
	v_exp_f32_e32 v73, v73
	v_pk_mul_f32 v[58:59], v[62:63], v[58:59]
	v_pk_add_f32 v[70:71], v[70:71], 1.0 op_sel_hi:[1,0]
	v_mul_f32_e32 v66, v66, v66
	v_rcp_f32_e32 v70, v70
	v_rcp_f32_e32 v71, v71
	v_pk_add_f32 v[62:63], v[72:73], 1.0 op_sel_hi:[1,0]
	v_pk_mul_f32 v[56:57], v[60:61], v[56:57]
	v_rcp_f32_e32 v62, v62
	v_rcp_f32_e32 v63, v63
	v_pk_mul_f32 v[60:61], v[66:67], v[70:71] op_sel_hi:[0,1]
	v_pk_mul_f32 v[70:71], v[52:53], v[68:69] op_sel_hi:[1,0]
	v_pk_mul_f32 v[56:57], v[56:57], v[60:61]
	v_exp_f32_e32 v70, v70
	v_exp_f32_e32 v71, v71
	v_pk_mul_f32 v[60:61], v[66:67], v[62:63] op_sel_hi:[0,1]
	v_pk_mul_f32 v[62:63], v[54:55], v[68:69] op_sel_hi:[1,0]
	v_pk_mul_f32 v[58:59], v[58:59], v[60:61]
	v_exp_f32_e32 v62, v62
	v_exp_f32_e32 v63, v63
	v_pk_add_f32 v[60:61], v[70:71], 1.0 op_sel_hi:[1,0]
	v_pk_mul_f32 v[50:51], v[54:55], v[50:51]
	v_rcp_f32_e32 v60, v60
	v_rcp_f32_e32 v61, v61
	v_pk_add_f32 v[54:55], v[62:63], 1.0 op_sel_hi:[1,0]
	v_pk_mul_f32 v[48:49], v[52:53], v[48:49]
	v_rcp_f32_e32 v54, v54
	v_rcp_f32_e32 v55, v55
	v_pk_mul_f32 v[52:53], v[66:67], v[60:61] op_sel_hi:[0,1]
	v_pk_mul_f32 v[52:53], v[48:49], v[52:53]
	v_pk_mul_f32 v[48:49], v[66:67], v[54:55] op_sel_hi:[0,1]
	v_pk_mul_f32 v[54:55], v[50:51], v[48:49]
	v_cvt_pk_bf16_f32 v48, v56, v57
	v_cvt_pk_bf16_f32 v49, v58, v59
	v_cvt_pk_bf16_f32 v50, v52, v53
	v_mad_u64_u32 v[52:53], s[10:11], v64, s47, v[200:201]
	v_cvt_pk_bf16_f32 v51, v54, v55
	global_store_dwordx4 v[52:53], v[48:51], off
	s_nop 1
	s_nop 0
	v_add_u32_e32 v48, 0x90, v138
	v_mov_b32_e32 v50, v207
	v_mul_f32_e32 v52, 0xbfb8aa3b, v50
	v_pk_mul_f32 v[54:55], v[44:45], v[52:53] op_sel_hi:[1,0]
	v_pk_mul_f32 v[56:57], v[46:47], v[52:53] op_sel_hi:[1,0]
	v_exp_f32_e32 v54, v54
	v_exp_f32_e32 v55, v55
	v_exp_f32_e32 v56, v56
	v_exp_f32_e32 v57, v57
	v_pk_mul_f32 v[42:43], v[46:47], v[42:43]
	v_pk_add_f32 v[54:55], v[54:55], 1.0 op_sel_hi:[1,0]
	v_mul_f32_e32 v50, v50, v50
	v_rcp_f32_e32 v54, v54
	v_rcp_f32_e32 v55, v55
	v_pk_add_f32 v[46:47], v[56:57], 1.0 op_sel_hi:[1,0]
	v_pk_mul_f32 v[40:41], v[44:45], v[40:41]
	v_rcp_f32_e32 v46, v46
	v_rcp_f32_e32 v47, v47
; __device__ __forceinline__ unsigned cvt_pk_bf16(float lo, float hi) { unsigned r; asm volatile("v_cvt_pk_bf16_f32 %0, %1, %2" : "=v"(r) : "v"(lo), "v"(hi)); return r; }
; __device__ __forceinline__ f32x2 swiglu_pk(f32x2 g, f32x2 u, float c, float r2) {
;     const f32x2 t = g * c;
;     f32x2 e; e.x = __builtin_amdgcn_exp2f(t.x); e.y = __builtin_amdgcn_exp2f(t.y);
;     const f32x2 d = e + 1.0f;
;     f32x2 s; s.x = __builtin_amdgcn_rcpf(d.x); s.y = __builtin_amdgcn_rcpf(d.y);
;     return (g * u) * (s * r2);
; }
;     __device__ __forceinline__ void operator()(const f32x4 (&acc)[2][2][4][2], const Unit& u, int wr, int wc, int fr, int fq) const {
;     ...
;                 const int row = row0 + ai * HALF + m * 16; const float r = tab ? rtab[row - u.pm * BM] : row_rstd(ss, row);
;                 const float c = r * -1.4426950408889634f, r2 = r * r;
;                 const f32x4 G0 = acc[ai][0][m][0], G1 = acc[ai][0][m][1], U0 = acc[ai][1][m][0], U1 = acc[ai][1][m][1];
;                 const f32x2 h0 = swiglu_pk((f32x2){G0[0], G0[1]}, (f32x2){U0[0], U0[1]}, c, r2), h1 = swiglu_pk((f32x2){G0[2], G0[3]}, (f32x2){U0[2], U0[3]}, c, r2);
;                 const f32x2 h2 = swiglu_pk((f32x2){G1[0], G1[1]}, (f32x2){U1[0], U1[1]}, c, r2), h3 = swiglu_pk((f32x2){G1[2], G1[3]}, (f32x2){U1[2], U1[3]}, c, r2);
;                 u32x4 w;
;                 w.x = cvt_pk_bf16(h0.x, h0.y); w.y = cvt_pk_bf16(h1.x, h1.y); w.z = cvt_pk_bf16(h2.x, h2.y); w.w = cvt_pk_bf16(h3.x, h3.y);
;                 *(u32x4*)(H + (size_t)row * ldh + col0) = w;
	v_pk_mul_f32 v[44:45], v[50:51], v[54:55] op_sel_hi:[0,1]
	v_pk_mul_f32 v[54:55], v[36:37], v[52:53] op_sel_hi:[1,0]
	v_pk_mul_f32 v[40:41], v[40:41], v[44:45]
	v_exp_f32_e32 v54, v54
	v_exp_f32_e32 v55, v55
	v_pk_mul_f32 v[44:45], v[50:51], v[46:47] op_sel_hi:[0,1]
	v_pk_mul_f32 v[46:47], v[38:39], v[52:53] op_sel_hi:[1,0]
	v_pk_mul_f32 v[42:43], v[42:43], v[44:45]
	v_exp_f32_e32 v46, v46
	v_exp_f32_e32 v47, v47
	v_pk_add_f32 v[44:45], v[54:55], 1.0 op_sel_hi:[1,0]
	v_pk_mul_f32 v[34:35], v[38:39], v[34:35]
	v_rcp_f32_e32 v44, v44
	v_rcp_f32_e32 v45, v45
	v_pk_add_f32 v[38:39], v[46:47], 1.0 op_sel_hi:[1,0]
	v_pk_mul_f32 v[32:33], v[36:37], v[32:33]
	v_rcp_f32_e32 v38, v38
	v_rcp_f32_e32 v39, v39
	v_pk_mul_f32 v[36:37], v[50:51], v[44:45] op_sel_hi:[0,1]
	v_pk_mul_f32 v[36:37], v[32:33], v[36:37]
	v_pk_mul_f32 v[32:33], v[50:51], v[38:39] op_sel_hi:[0,1]
	v_pk_mul_f32 v[38:39], v[34:35], v[32:33]
	v_cvt_pk_bf16_f32 v32, v40, v41
	v_cvt_pk_bf16_f32 v33, v42, v43
	v_cvt_pk_bf16_f32 v34, v36, v37
	v_mad_u64_u32 v[36:37], s[10:11], v48, s47, v[200:201]
	v_cvt_pk_bf16_f32 v35, v38, v39
	global_store_dwordx4 v[36:37], v[32:35], off
	s_nop 1
	s_nop 0
	v_add_u32_e32 v32, 0xa0, v138
	v_mov_b32_e32 v34, v208
	v_mul_f32_e32 v36, 0xbfb8aa3b, v34
	v_pk_mul_f32 v[38:39], v[28:29], v[36:37] op_sel_hi:[1,0]
	v_pk_mul_f32 v[40:41], v[30:31], v[36:37] op_sel_hi:[1,0]
	v_exp_f32_e32 v38, v38
	v_exp_f32_e32 v39, v39
	v_exp_f32_e32 v40, v40
	v_exp_f32_e32 v41, v41
	v_pk_mul_f32 v[26:27], v[30:31], v[26:27]
	v_pk_add_f32 v[38:39], v[38:39], 1.0 op_sel_hi:[1,0]
	v_mul_f32_e32 v34, v34, v34
	v_rcp_f32_e32 v38, v38
	v_rcp_f32_e32 v39, v39
	v_pk_add_f32 v[30:31], v[40:41], 1.0 op_sel_hi:[1,0]
	v_pk_mul_f32 v[24:25], v[28:29], v[24:25]
	v_rcp_f32_e32 v30, v30
	v_rcp_f32_e32 v31, v31
	v_pk_mul_f32 v[28:29], v[34:35], v[38:39] op_sel_hi:[0,1]
	v_pk_mul_f32 v[38:39], v[20:21], v[36:37] op_sel_hi:[1,0]
	v_pk_mul_f32 v[24:25], v[24:25], v[28:29]
	v_exp_f32_e32 v38, v38
	v_exp_f32_e32 v39, v39
	v_pk_mul_f32 v[28:29], v[34:35], v[30:31] op_sel_hi:[0,1]
	v_pk_mul_f32 v[30:31], v[22:23], v[36:37] op_sel_hi:[1,0]
	v_pk_mul_f32 v[26:27], v[26:27], v[28:29]
	v_exp_f32_e32 v30, v30
	v_exp_f32_e32 v31, v31
	v_pk_add_f32 v[28:29], v[38:39], 1.0 op_sel_hi:[1,0]
	v_pk_mul_f32 v[18:19], v[22:23], v[18:19]
	v_rcp_f32_e32 v28, v28
	v_rcp_f32_e32 v29, v29
	v_pk_add_f32 v[22:23], v[30:31], 1.0 op_sel_hi:[1,0]
	v_pk_mul_f32 v[16:17], v[20:21], v[16:17]
	v_rcp_f32_e32 v22, v22
	v_rcp_f32_e32 v23, v23
	v_pk_mul_f32 v[20:21], v[34:35], v[28:29] op_sel_hi:[0,1]
	v_pk_mul_f32 v[20:21], v[16:17], v[20:21]
	v_pk_mul_f32 v[16:17], v[34:35], v[22:23] op_sel_hi:[0,1]
	v_pk_mul_f32 v[22:23], v[18:19], v[16:17]
	v_cvt_pk_bf16_f32 v16, v24, v25
	v_cvt_pk_bf16_f32 v17, v26, v27
	v_cvt_pk_bf16_f32 v18, v20, v21
	v_mad_u64_u32 v[20:21], s[10:11], v32, s47, v[200:201]
	v_cvt_pk_bf16_f32 v19, v22, v23
	global_store_dwordx4 v[20:21], v[16:19], off
	s_nop 1
	s_nop 0
	v_add_u32_e32 v16, 0xb0, v138
	v_mov_b32_e32 v18, v209
	v_mul_f32_e32 v20, 0xbfb8aa3b, v18
	v_pk_mul_f32 v[22:23], v[12:13], v[20:21] op_sel_hi:[1,0]
	v_pk_mul_f32 v[24:25], v[14:15], v[20:21] op_sel_hi:[1,0]
	v_exp_f32_e32 v22, v22
	v_exp_f32_e32 v23, v23
	v_exp_f32_e32 v24, v24
	v_exp_f32_e32 v25, v25
	v_pk_mul_f32 v[10:11], v[14:15], v[10:11]
	v_pk_add_f32 v[22:23], v[22:23], 1.0 op_sel_hi:[1,0]
	v_mul_f32_e32 v18, v18, v18
	v_rcp_f32_e32 v22, v22
	v_rcp_f32_e32 v23, v23
	v_pk_add_f32 v[14:15], v[24:25], 1.0 op_sel_hi:[1,0]
	v_pk_mul_f32 v[8:9], v[12:13], v[8:9]
	v_rcp_f32_e32 v14, v14
	v_rcp_f32_e32 v15, v15
	v_pk_mul_f32 v[12:13], v[18:19], v[22:23] op_sel_hi:[0,1]
	v_pk_mul_f32 v[22:23], v[4:5], v[20:21] op_sel_hi:[1,0]
	v_pk_mul_f32 v[8:9], v[8:9], v[12:13]
	v_exp_f32_e32 v22, v22
	v_exp_f32_e32 v23, v23
	v_pk_mul_f32 v[12:13], v[18:19], v[14:15] op_sel_hi:[0,1]
	v_pk_mul_f32 v[14:15], v[6:7], v[20:21] op_sel_hi:[1,0]
	v_pk_mul_f32 v[10:11], v[10:11], v[12:13]
	v_exp_f32_e32 v14, v14
	v_exp_f32_e32 v15, v15
	v_pk_add_f32 v[12:13], v[22:23], 1.0 op_sel_hi:[1,0]
	v_pk_mul_f32 v[2:3], v[6:7], v[2:3]
	v_rcp_f32_e32 v12, v12
	v_rcp_f32_e32 v13, v13
	v_pk_add_f32 v[6:7], v[14:15], 1.0 op_sel_hi:[1,0]
	v_pk_mul_f32 v[0:1], v[4:5], v[0:1]
	v_rcp_f32_e32 v6, v6
	v_rcp_f32_e32 v7, v7
	v_pk_mul_f32 v[4:5], v[18:19], v[12:13] op_sel_hi:[0,1]
	v_pk_mul_f32 v[4:5], v[0:1], v[4:5]
	s_andn2_b64 vcc, exec, s[8:9]
	v_pk_mul_f32 v[0:1], v[18:19], v[6:7] op_sel_hi:[0,1]
	v_pk_mul_f32 v[6:7], v[2:3], v[0:1]
	v_cvt_pk_bf16_f32 v0, v8, v9
	v_cvt_pk_bf16_f32 v1, v10, v11
	v_cvt_pk_bf16_f32 v2, v4, v5
	v_mad_u64_u32 v[4:5], s[0:1], v16, s47, v[200:201]
	v_cvt_pk_bf16_f32 v3, v6, v7
	s_mov_b64 s[0:1], -1
	global_store_dwordx4 v[4:5], v[0:3], off
	s_nop 1
	s_branch .Ljoin_p8

; #define PG8_BAR __builtin_amdgcn_s_barrier()
; template <class Epi, class Sched, bool ALIGN_EPI = false, bool SP2 = false>
; __device__ __forceinline__ void gemm_phase(PG8_LAS unsigned char* lds, const Gemm g, const Sched& S, const Epi& E) {
;     ...
;         if (!has_next) break;
; #pragma unroll
;         for (int a = 0; a < 2; ++a)
; #pragma unroll
;             for (int b = 0; b < 2; ++b)
; #pragma unroll
;                 for (int m = 0; m < 4; ++m)
; #pragma unroll
;                     for (int n = 0; n < 2; ++n) acc[a][b][m][n] = (f32x4){0.f, 0.f, 0.f, 0.f};
;         cur = nxt; cA = nA; cB = nB; ++ui;
;         if constexpr (ALIGN_EPI) { if (wr == 1) PG8_BAR; }
.Ljoin_p8:
	s_cbranch_vccnz .LBB0_1318
	s_andn2_b64 vcc, exec, s[4:5]
	s_cbranch_vccnz .LBB0_1317
	s_barrier
	s_branch .LBB0_1317
